# attention tile loop: K/V LDS-DMA issue in the QK result-latency gap (replaces s_nop 10) and the fetch-ahead test rotated in front of the per-tile barrier (loop head now starts the fragment reads)
# speedup vs baseline: 1.0057x; 1.0057x over previous
.LBB0_567:
	s_or_b64 exec, exec, s[18:19]
	s_waitcnt vmcnt(4)
	v_add_f32_e32 v0, 0, v86
	s_mov_b32 s1, 1
	s_mov_b32 s17, 1
	s_mov_b32 s22, 1
	s_cmp_ge_u32 s22, s13
	s_cselect_b64 s[18:19], -1, 0
	s_barrier
	s_branch .LBB0_569
.LBB0_568:
	s_add_i32 s18, s1, 1
	s_cmp_lg_u32 s1, 2
	s_cselect_b32 s1, s18, 0
	s_add_i32 s17, s17, 1
	s_and_b32 s17, s17, 3
	s_add_i32 s22, s22, 1
	s_cmp_ge_u32 s22, s13
	s_cselect_b64 s[18:19], -1, 0
	v_add_f32_e32 v0, v0, v83
	s_cmp_eq_u32 s68, s22
	s_barrier
	s_cbranch_scc1 .LBB0_579
.LBB0_569:
.LBB0_571:
	v_lshl_add_u32 v82, s1, 14, v157
	s_and_saveexec_b64 s[20:21], s[6:7]
	s_xor_b64 s[20:21], exec, s[20:21]
	s_cbranch_execz .LBB0_575
	s_lshl_b32 s23, s17, 14
	s_add_i32 s23, s23, 0xc000
	s_and_b32 s23, s23, 0xc000
	v_add_u32_e32 v83, s23, v157
	v_add_u32_e32 v96, v83, v171
	ds_read_b128 v[84:87], v96 offset:49152
	ds_read_b128 v[88:91], v96 offset:53248
	ds_read_b128 v[92:95], v96 offset:57344
	ds_read_b128 v[146:149], v96 offset:61440
	v_add_u32_e32 v96, v83, v170
	ds_read_b128 v[180:183], v96 offset:49152
	ds_read_b128 v[184:187], v96 offset:53248
	ds_read_b128 v[188:191], v96 offset:57344
	ds_read_b128 v[206:209], v96 offset:61440
	v_add_u32_e32 v96, v83, v169
	v_add_u32_e32 v83, v83, v168
	ds_read_b128 v[210:213], v96 offset:49152
	ds_read_b128 v[214:217], v96 offset:53248
	ds_read_b128 v[218:221], v96 offset:57344
	ds_read_b128 v[222:225], v96 offset:61440
	ds_read_b128 v[226:229], v83 offset:49152
	ds_read_b128 v[230:233], v83 offset:53248
	ds_read_b128 v[234:237], v83 offset:57344
	ds_read_b128 v[238:241], v83 offset:61440
	s_waitcnt lgkmcnt(0)
	v_mfma_f32_32x32x16_bf16 v[50:65], v[84:87], v[66:69], v[50:65]
	v_mfma_f32_32x32x16_bf16 v[34:49], v[88:91], v[66:69], v[34:49]
	v_mfma_f32_32x32x16_bf16 v[18:33], v[92:95], v[66:69], v[18:33]
	v_mfma_f32_32x32x16_bf16 v[2:17], v[146:149], v[66:69], v[2:17]
	v_mfma_f32_32x32x16_bf16 v[50:65], v[180:183], v[70:73], v[50:65]
	v_mfma_f32_32x32x16_bf16 v[34:49], v[184:187], v[70:73], v[34:49]
	v_mfma_f32_32x32x16_bf16 v[18:33], v[188:191], v[70:73], v[18:33]
	v_mfma_f32_32x32x16_bf16 v[2:17], v[206:209], v[70:73], v[2:17]
	v_mfma_f32_32x32x16_bf16 v[50:65], v[210:213], v[74:77], v[50:65]
	v_mfma_f32_32x32x16_bf16 v[34:49], v[214:217], v[74:77], v[34:49]
	v_mfma_f32_32x32x16_bf16 v[18:33], v[218:221], v[74:77], v[18:33]
	v_mfma_f32_32x32x16_bf16 v[2:17], v[222:225], v[74:77], v[2:17]
	v_mfma_f32_32x32x16_bf16 v[50:65], v[226:229], v[78:81], v[50:65]
	v_mfma_f32_32x32x16_bf16 v[34:49], v[230:233], v[78:81], v[34:49]
	v_mfma_f32_32x32x16_bf16 v[18:33], v[234:237], v[78:81], v[18:33]
	v_mfma_f32_32x32x16_bf16 v[2:17], v[238:241], v[78:81], v[2:17]
	v_add_u32_e32 v70, v82, v171
	v_add_u32_e32 v74, v82, v170
	v_add_u32_e32 v75, v82, v169
	v_add_u32_e32 v76, v82, v168
	ds_read_b128 v[66:69], v70 offset:8192
	ds_read_b128 v[70:73], v70 offset:12288
	ds_read_b128 v[146:149], v74 offset:8192
	ds_read_b128 v[180:183], v74 offset:12288
	ds_read_b128 v[184:187], v75 offset:8192
	ds_read_b128 v[188:191], v75 offset:12288
	ds_read_b128 v[206:209], v76 offset:8192
	ds_read_b128 v[210:213], v76 offset:12288
	s_waitcnt lgkmcnt(0)
	v_mfma_f32_32x32x16_bf16 v[82:97], v[66:69], v[98:101], 0
	v_mfma_f32_32x32x16_bf16 v[66:81], v[70:73], v[98:101], 0
	v_mfma_f32_32x32x16_bf16 v[82:97], v[146:149], v[102:105], v[82:97]
	v_mfma_f32_32x32x16_bf16 v[66:81], v[180:183], v[102:105], v[66:81]
	v_mfma_f32_32x32x16_bf16 v[82:97], v[184:187], v[106:109], v[82:97]
	v_mfma_f32_32x32x16_bf16 v[66:81], v[188:191], v[106:109], v[66:81]
	v_mfma_f32_32x32x16_bf16 v[82:97], v[206:209], v[110:113], v[82:97]
	v_mfma_f32_32x32x16_bf16 v[66:81], v[210:213], v[110:113], v[66:81]
	s_and_b64 vcc, exec, s[18:19]
	s_cbranch_vccnz .Lmy_nodma_m1
	s_lshl_b32 vcc_lo, s1, 14
	s_addk_i32 vcc_lo, 0xc000
	s_cmp_lg_u32 s1, 0
	s_cselect_b32 vcc_lo, vcc_lo, 0x8000
	s_add_i32 vcc_lo, vcc_lo, s100
	s_lshl_b32 s101, s17, 14
	s_mov_b32 m0, vcc_lo
	s_xor_b32 s101, s101, 0x8000
	s_add_i32 s101, s101, s100
	global_load_lds_dwordx4 v[144:145], off
	v_lshl_add_u64 v[246:247], v[144:145], 0, s[38:39]
	s_add_i32 m0, vcc_lo, 0x2000
	s_add_i32 vcc_lo, s101, 0xc000
	global_load_lds_dwordx4 v[246:247], off
	s_mov_b32 m0, vcc_lo
	s_add_i32 vcc_lo, s101, 0xe000
	global_load_lds_dwordx4 v[140:141], off
	s_mov_b32 m0, vcc_lo
	s_add_i32 s69, s69, 1
	global_load_lds_dwordx4 v[142:143], off
	s_cmp_eq_u32 s69, 32
	v_lshl_add_u64 v[246:247], v[144:145], 0, s[30:31]
	s_cselect_b64 vcc, -1, 0
	v_lshl_add_u64 v[140:141], v[140:141], 0, s[38:39]
	v_lshl_add_u64 v[142:143], v[142:143], 0, s[38:39]
	v_cndmask_b32_e32 v145, v247, v139, vcc
	v_cndmask_b32_e32 v144, v246, v138, vcc
	s_branch .Lmy_dmadone_m1
.Lmy_nodma_m1:
	s_nop 10
.Lmy_dmadone_m1:
	v_exp_f32_e32 v82, v82
	v_exp_f32_e32 v83, v83
	v_exp_f32_e32 v84, v84
	v_exp_f32_e32 v85, v85
	v_add_f32_e32 v135, 0, v82
	v_exp_f32_e32 v86, v86
	v_add_f32_e32 v135, v83, v135
	v_exp_f32_e32 v87, v87
	v_add_f32_e32 v135, v84, v135
	v_exp_f32_e32 v88, v88
	v_add_f32_e32 v135, v85, v135
	v_exp_f32_e32 v89, v89
	v_add_f32_e32 v135, v86, v135
	v_exp_f32_e32 v90, v90
	v_add_f32_e32 v135, v87, v135
	v_exp_f32_e32 v91, v91
	v_add_f32_e32 v135, v88, v135
	v_exp_f32_e32 v92, v92
	v_add_f32_e32 v135, v89, v135
	v_exp_f32_e32 v93, v93
	v_add_f32_e32 v135, v90, v135
	v_exp_f32_e32 v94, v94
	v_add_f32_e32 v135, v91, v135
	v_exp_f32_e32 v95, v95
	v_add_f32_e32 v135, v92, v135
	v_exp_f32_e32 v96, v96
	v_add_f32_e32 v135, v93, v135
	v_exp_f32_e32 v97, v97
	v_add_f32_e32 v135, v94, v135
	v_exp_f32_e32 v137, v66
	v_add_f32_e32 v135, v95, v135
	v_exp_f32_e32 v146, v67
	v_add_f32_e32 v135, v96, v135
	v_exp_f32_e32 v147, v68
	v_add_f32_e32 v135, v97, v135
	v_exp_f32_e32 v148, v69
	v_exp_f32_e32 v149, v70
	v_cvt_pk_bf16_f32 v66, v82, v83
	v_add_f32_e32 v82, v137, v135
	v_exp_f32_e32 v150, v71
	v_add_f32_e32 v82, v146, v82
	v_exp_f32_e32 v151, v72
	v_add_f32_e32 v82, v147, v82
	v_exp_f32_e32 v180, v73
	v_add_f32_e32 v82, v148, v82
	v_exp_f32_e32 v181, v74
	v_add_f32_e32 v82, v149, v82
	v_exp_f32_e32 v182, v75
	v_add_f32_e32 v82, v150, v82
	v_exp_f32_e32 v183, v76
	v_add_f32_e32 v82, v151, v82
	v_exp_f32_e32 v184, v77
	v_add_f32_e32 v82, v180, v82
	v_exp_f32_e32 v185, v78
	v_add_f32_e32 v82, v181, v82
	v_exp_f32_e32 v186, v79
	v_add_f32_e32 v82, v182, v82
	v_exp_f32_e32 v187, v80
	v_add_f32_e32 v82, v183, v82
	v_exp_f32_e32 v188, v81
	v_add_f32_e32 v82, v184, v82
	v_add_f32_e32 v82, v185, v82
	v_add_f32_e32 v82, v186, v82
	v_add_f32_e32 v82, v187, v82
	v_cvt_pk_bf16_f32 v67, v84, v85
	v_cvt_pk_bf16_f32 v68, v86, v87
	v_cvt_pk_bf16_f32 v69, v88, v89
	v_cvt_pk_bf16_f32 v70, v90, v91
	v_cvt_pk_bf16_f32 v71, v92, v93
	v_cvt_pk_bf16_f32 v72, v94, v95
	v_cvt_pk_bf16_f32 v73, v96, v97
	v_cvt_pk_bf16_f32 v74, v137, v146
	v_cvt_pk_bf16_f32 v75, v147, v148
	v_cvt_pk_bf16_f32 v76, v149, v150
	v_cvt_pk_bf16_f32 v77, v151, v180
	v_cvt_pk_bf16_f32 v78, v181, v182
	v_cvt_pk_bf16_f32 v79, v183, v184
	v_cvt_pk_bf16_f32 v80, v185, v186
	v_cvt_pk_bf16_f32 v81, v187, v188
	v_add_f32_e32 v83, v188, v82
	s_andn2_saveexec_b64 s[20:21], s[20:21]
	s_cbranch_execnz .LBB0_576

.LBB0_576:
	v_add_u32_e32 v70, v82, v171
	v_add_u32_e32 v74, v82, v170
	v_add_u32_e32 v75, v82, v169
	v_add_u32_e32 v76, v82, v168
	ds_read_b128 v[66:69], v70
	ds_read_b128 v[70:73], v70 offset:4096
	ds_read_b128 v[146:149], v74
	ds_read_b128 v[180:183], v74 offset:4096
	ds_read_b128 v[184:187], v75
	ds_read_b128 v[188:191], v75 offset:4096
	ds_read_b128 v[206:209], v76
	ds_read_b128 v[210:213], v76 offset:4096
	s_waitcnt lgkmcnt(0)
	v_mfma_f32_32x32x16_bf16 v[82:97], v[66:69], v[98:101], 0
	v_mfma_f32_32x32x16_bf16 v[66:81], v[70:73], v[98:101], 0
	v_mfma_f32_32x32x16_bf16 v[82:97], v[146:149], v[102:105], v[82:97]
	v_mfma_f32_32x32x16_bf16 v[66:81], v[180:183], v[102:105], v[66:81]
	v_mfma_f32_32x32x16_bf16 v[82:97], v[184:187], v[106:109], v[82:97]
	v_mfma_f32_32x32x16_bf16 v[66:81], v[188:191], v[106:109], v[66:81]
	v_mfma_f32_32x32x16_bf16 v[82:97], v[206:209], v[110:113], v[82:97]
	v_mfma_f32_32x32x16_bf16 v[66:81], v[210:213], v[110:113], v[66:81]
	s_and_b64 vcc, exec, s[18:19]
	s_cbranch_vccnz .Lmy_nodma_m0
	s_lshl_b32 vcc_lo, s1, 14
	s_addk_i32 vcc_lo, 0xc000
	s_cmp_lg_u32 s1, 0
	s_cselect_b32 vcc_lo, vcc_lo, 0x8000
	s_add_i32 vcc_lo, vcc_lo, s100
	s_lshl_b32 s101, s17, 14
	s_mov_b32 m0, vcc_lo
	s_xor_b32 s101, s101, 0x8000
	s_add_i32 s101, s101, s100
	global_load_lds_dwordx4 v[144:145], off
	v_lshl_add_u64 v[246:247], v[144:145], 0, s[38:39]
	s_add_i32 m0, vcc_lo, 0x2000
	s_add_i32 vcc_lo, s101, 0xc000
	global_load_lds_dwordx4 v[246:247], off
	s_mov_b32 m0, vcc_lo
	s_add_i32 vcc_lo, s101, 0xe000
	global_load_lds_dwordx4 v[140:141], off
	s_mov_b32 m0, vcc_lo
	s_add_i32 s69, s69, 1
	global_load_lds_dwordx4 v[142:143], off
	s_cmp_eq_u32 s69, 32
	v_lshl_add_u64 v[246:247], v[144:145], 0, s[30:31]
	s_cselect_b64 vcc, -1, 0
	v_lshl_add_u64 v[140:141], v[140:141], 0, s[38:39]
	v_lshl_add_u64 v[142:143], v[142:143], 0, s[38:39]
	v_cndmask_b32_e32 v145, v247, v139, vcc
	v_cndmask_b32_e32 v144, v246, v138, vcc
	s_branch .Lmy_dmadone_m0

.Lmy_dmadone_m0:
	v_exp_f32_e32 v82, v82
	v_exp_f32_e32 v83, v83
	v_exp_f32_e32 v84, v84
	v_exp_f32_e32 v85, v85
	v_add_f32_e32 v135, 0, v82
	v_exp_f32_e32 v86, v86
	v_add_f32_e32 v135, v83, v135
	v_exp_f32_e32 v87, v87
	v_add_f32_e32 v135, v84, v135
	v_exp_f32_e32 v88, v88
	v_add_f32_e32 v135, v85, v135
	v_exp_f32_e32 v89, v89
	v_add_f32_e32 v135, v86, v135
	v_exp_f32_e32 v90, v90
	v_add_f32_e32 v135, v87, v135
	v_exp_f32_e32 v91, v91
	v_add_f32_e32 v135, v88, v135
	v_exp_f32_e32 v92, v92
	v_add_f32_e32 v135, v89, v135
	v_exp_f32_e32 v93, v93
	v_add_f32_e32 v135, v90, v135
	v_exp_f32_e32 v94, v94
	v_add_f32_e32 v135, v91, v135
	v_exp_f32_e32 v95, v95
	v_add_f32_e32 v135, v92, v135
	v_exp_f32_e32 v96, v96
	v_add_f32_e32 v135, v93, v135
	v_exp_f32_e32 v97, v97
	v_add_f32_e32 v135, v94, v135
	v_exp_f32_e32 v137, v66
	v_add_f32_e32 v135, v95, v135
	v_exp_f32_e32 v146, v67
	v_add_f32_e32 v135, v96, v135
	v_exp_f32_e32 v147, v68
	v_add_f32_e32 v135, v97, v135
	v_exp_f32_e32 v148, v69
	v_exp_f32_e32 v149, v70
	v_cvt_pk_bf16_f32 v66, v82, v83
	v_add_f32_e32 v82, v137, v135
	v_exp_f32_e32 v150, v71
	v_add_f32_e32 v82, v146, v82
	v_exp_f32_e32 v151, v72
	v_add_f32_e32 v82, v147, v82
	v_exp_f32_e32 v180, v73
	v_add_f32_e32 v82, v148, v82
	v_exp_f32_e32 v181, v74
	v_add_f32_e32 v82, v149, v82
	v_exp_f32_e32 v182, v75
	v_add_f32_e32 v82, v150, v82
	v_exp_f32_e32 v183, v76
	v_add_f32_e32 v82, v151, v82
	v_exp_f32_e32 v184, v77
	v_add_f32_e32 v82, v180, v82
	v_exp_f32_e32 v185, v78
	v_add_f32_e32 v82, v181, v82
	v_exp_f32_e32 v186, v79
	v_add_f32_e32 v82, v182, v82
	v_exp_f32_e32 v187, v80
	v_exp_f32_e32 v192, v81
	v_add_f32_e32 v82, v183, v82
	v_add_f32_e32 v82, v184, v82
	v_cvt_pk_bf16_f32 v74, v137, v146
	v_add_f32_e32 v82, v185, v82
	v_lshl_add_u32 v137, s17, 14, v157
	v_cvt_pk_bf16_f32 v72, v94, v95
	v_cvt_pk_bf16_f32 v76, v149, v150
	v_add_f32_e32 v82, v186, v82
	v_add_u32_e32 v94, v137, v171
	v_add_u32_e32 v150, v137, v170
	v_cvt_pk_bf16_f32 v67, v84, v85
	v_cvt_pk_bf16_f32 v68, v86, v87
	v_cvt_pk_bf16_f32 v69, v88, v89
	v_cvt_pk_bf16_f32 v70, v90, v91
	v_cvt_pk_bf16_f32 v71, v92, v93
	v_cvt_pk_bf16_f32 v73, v96, v97
	v_cvt_pk_bf16_f32 v75, v147, v148
	v_cvt_pk_bf16_f32 v77, v151, v180
	v_cvt_pk_bf16_f32 v78, v181, v182
	v_cvt_pk_bf16_f32 v79, v183, v184
	v_cvt_pk_bf16_f32 v80, v185, v186
	v_cvt_pk_bf16_f32 v81, v187, v192
	v_add_f32_e32 v135, v187, v82
	ds_read_b128 v[82:85], v94 offset:49152
	ds_read_b128 v[86:89], v94 offset:53248
	ds_read_b128 v[90:93], v94 offset:57344
	ds_read_b128 v[94:97], v94 offset:61440
	ds_read_b128 v[146:149], v150 offset:49152
	ds_read_b128 v[180:183], v150 offset:53248
	ds_read_b128 v[184:187], v150 offset:57344
	ds_read_b128 v[188:191], v150 offset:61440
	v_add_u32_e32 v150, v137, v169
	v_add_u32_e32 v137, v137, v168
	ds_read_b128 v[206:209], v150 offset:49152
	ds_read_b128 v[210:213], v150 offset:53248
	ds_read_b128 v[214:217], v150 offset:57344
	ds_read_b128 v[218:221], v150 offset:61440
	ds_read_b128 v[222:225], v137 offset:49152
	ds_read_b128 v[226:229], v137 offset:53248
	ds_read_b128 v[230:233], v137 offset:57344
	ds_read_b128 v[234:237], v137 offset:61440
	s_waitcnt lgkmcnt(0)
	v_mfma_f32_32x32x16_bf16 v[50:65], v[82:85], v[66:69], v[50:65]
	v_add_f32_e32 v83, v192, v135
	v_mfma_f32_32x32x16_bf16 v[34:49], v[86:89], v[66:69], v[34:49]
	v_mfma_f32_32x32x16_bf16 v[18:33], v[90:93], v[66:69], v[18:33]
	v_mfma_f32_32x32x16_bf16 v[2:17], v[94:97], v[66:69], v[2:17]
	v_mfma_f32_32x32x16_bf16 v[50:65], v[146:149], v[70:73], v[50:65]
	v_mfma_f32_32x32x16_bf16 v[34:49], v[180:183], v[70:73], v[34:49]
	v_mfma_f32_32x32x16_bf16 v[18:33], v[184:187], v[70:73], v[18:33]
	v_mfma_f32_32x32x16_bf16 v[2:17], v[188:191], v[70:73], v[2:17]
	v_mfma_f32_32x32x16_bf16 v[50:65], v[206:209], v[74:77], v[50:65]
	v_mfma_f32_32x32x16_bf16 v[34:49], v[210:213], v[74:77], v[34:49]
	v_mfma_f32_32x32x16_bf16 v[18:33], v[214:217], v[74:77], v[18:33]
	v_mfma_f32_32x32x16_bf16 v[2:17], v[218:221], v[74:77], v[2:17]
	v_mfma_f32_32x32x16_bf16 v[50:65], v[222:225], v[78:81], v[50:65]
	v_mfma_f32_32x32x16_bf16 v[34:49], v[226:229], v[78:81], v[34:49]
	v_mfma_f32_32x32x16_bf16 v[18:33], v[230:233], v[78:81], v[18:33]
	v_mfma_f32_32x32x16_bf16 v[2:17], v[234:237], v[78:81], v[2:17]
	s_or_b64 exec, exec, s[20:21]
	s_mov_b64 s[20:21], -1
	s_and_b64 vcc, exec, s[18:19]
	s_cbranch_vccnz .LBB0_574
